# speedup vs baseline: 1.0382x; 1.0225x over previous
; __device__ __forceinline__ float bf2f(bf16_t b) { return __uint_as_float(((unsigned)b) << 16); }
; __global__ void __launch_bounds__(NTHREADS) fwd_megakernel(Params p) {
;     ...
;             const int e = (id - n_scan) * 256 + tid;
;             const int t = e >> 5, c0 = (e & 31) * 8;
;             const int w = 2 << (c0 >> 6);
;             int pos, L;
;             if (t < NPROMPT) { pos = t & 2047; L = 2048; } else { pos = (t - NPROMPT) & 4095; L = 4096; }
;             int lo = pos - (w >> 1), hi = lo + w;
;             if (lo < 0) lo = 0;
;             if (hi > L) hi = L;
;             float sum[8];
; #pragma unroll
;             for (int j = 0; j < 8; ++j) sum[j] = 0.f;
;             const bf16_t* base = p.pbuf + (long)(t - pos) * 256 + c0;
;             for (int k = lo; k < hi; ++k) {
;               bf16x8 v = *reinterpret_cast<const bf16x8*>(base + (long)k * 256);
; #pragma unroll
;               for (int j = 0; j < 8; ++j) sum[j] += bf2f((bf16_t)v[j]);
.LBB0_214:
	s_lshl_b32 s17, s9, 8
	s_cmpk_gt_i32 s9, 0x11f
	s_mov_b64 s[12:13], -1
	s_cbranch_scc0 .LBB0_220
	s_add_i32 s18, s17, 0xfffee000
	v_or_b32_e32 v13, s18, v215
	s_cmp_lt_u32 s18, 0x200000
	s_movk_i32 s12, 0x7ff
	v_lshrrev_b32_e32 v1, 5, v13
	s_cselect_b32 s12, s12, 0xfff
	v_and_b32_e32 v24, s12, v1
	v_sub_u32_e32 v0, v24, v119
	s_movk_i32 s12, 0x800
	v_max_i32_e32 v15, 0, v0
	s_cselect_b32 s12, s12, 0x1000
	v_add_u32_e32 v0, v0, v118
	v_min_i32_e32 v25, s12, v0
	v_mov_b32_e32 v21, 0
	v_cmp_gt_i32_e32 vcc, v25, v15
	v_lshlrev_b32_e32 v0, 9, v24
	v_mov_b32_e32 v20, v21
	v_mov_b32_e32 v19, v21
	v_mov_b32_e32 v18, v21
	v_mov_b32_e32 v17, v21
	v_mov_b32_e32 v16, v21
	v_mov_b32_e32 v3, v21
	v_mov_b32_e32 v2, v21
	s_and_saveexec_b64 s[12:13], vcc
	s_cbranch_execz .LBB0_219
	v_lshrrev_b32_e32 v152, 5, v123
	v_lshlrev_b64 v[2:3], 9, v[152:153]
	v_lshlrev_b32_e32 v152, 9, v15
	v_lshl_add_u64 v[2:3], v[2:3], 0, v[152:153]
	v_sub_co_u32_e32 v2, vcc, v2, v0
	s_mov_b64 s[14:15], 0
	s_nop 0
	v_subbrev_co_u32_e32 v3, vcc, 0, v3, vcc
	v_lshl_add_u64 v[22:23], v[10:11], 0, v[2:3]
	v_mov_b32_e32 v2, 0
	v_mov_b32_e32 v26, v15
	v_mov_b32_e32 v3, v2
	v_mov_b32_e32 v16, v2
	v_mov_b32_e32 v17, v2
	v_mov_b32_e32 v18, v2
	v_mov_b32_e32 v19, v2
	v_mov_b32_e32 v20, v2
	v_mov_b32_e32 v21, v2
	s_mov_b64 s[100:101], exec
	v_mov_b32_e32 v220, 0
	v_mov_b32_e32 v221, 0
	v_mov_b32_e32 v222, 0
	v_mov_b32_e32 v223, 0
	v_mov_b32_e32 v224, 0
	v_mov_b32_e32 v225, 0
	v_mov_b32_e32 v226, 0
	v_mov_b32_e32 v227, 0
	v_mov_b32_e32 v228, 0
	v_mov_b32_e32 v229, 0
	v_mov_b32_e32 v230, 0
	v_mov_b32_e32 v231, 0
	v_mov_b32_e32 v232, 0
	v_mov_b32_e32 v233, 0
	v_mov_b32_e32 v234, 0
	v_mov_b32_e32 v235, 0
	v_mov_b32_e32 v236, 0
	v_mov_b32_e32 v237, 0
	v_mov_b32_e32 v238, 0
	v_mov_b32_e32 v239, 0
	v_mov_b32_e32 v240, 0
	v_mov_b32_e32 v241, 0
	v_mov_b32_e32 v242, 0
	v_mov_b32_e32 v243, 0
	v_mov_b32_e32 v244, 0
	v_mov_b32_e32 v245, 0
	v_mov_b32_e32 v246, 0
	v_mov_b32_e32 v247, 0
	v_mov_b32_e32 v248, 0
	v_mov_b32_e32 v249, 0
	v_mov_b32_e32 v250, 0
	v_mov_b32_e32 v251, 0
	v_mov_b32_e32 v130, 0
	v_mov_b32_e32 v131, 0
	v_mov_b32_e32 v132, 0
	v_mov_b32_e32 v133, 0
	v_mov_b32_e32 v134, 0
	v_mov_b32_e32 v135, 0
	v_mov_b32_e32 v136, 0
	v_mov_b32_e32 v137, 0
	v_mov_b32_e32 v138, 0
	v_mov_b32_e32 v139, 0
	v_mov_b32_e32 v140, 0
	v_mov_b32_e32 v141, 0
	v_mov_b32_e32 v142, 0
	v_mov_b32_e32 v143, 0
	v_mov_b32_e32 v144, 0
	v_mov_b32_e32 v145, 0
	v_mov_b32_e32 v146, 0
	v_mov_b32_e32 v147, 0
	v_mov_b32_e32 v148, 0
	v_mov_b32_e32 v149, 0
	v_mov_b32_e32 v154, 0
	v_mov_b32_e32 v155, 0
	v_mov_b32_e32 v156, 0
	v_mov_b32_e32 v157, 0
	v_mov_b32_e32 v158, 0
	v_mov_b32_e32 v159, 0
	v_mov_b32_e32 v160, 0
	v_mov_b32_e32 v161, 0
	global_load_dwordx4 v[216:219], v[22:23], off
	v_add_u32_e32 v26, 1, v26
	v_cmp_lt_i32_e32 vcc, v26, v25
	v_lshl_add_u64 v[22:23], v[22:23], 0, s[92:93]
	s_and_b64 exec, exec, vcc
	global_load_dwordx4 v[220:223], v[22:23], off
	v_add_u32_e32 v26, 1, v26
	v_cmp_lt_i32_e32 vcc, v26, v25
	v_lshl_add_u64 v[22:23], v[22:23], 0, s[92:93]
	s_and_b64 exec, exec, vcc
	global_load_dwordx4 v[224:227], v[22:23], off
	v_add_u32_e32 v26, 1, v26
	v_cmp_lt_i32_e32 vcc, v26, v25
	v_lshl_add_u64 v[22:23], v[22:23], 0, s[92:93]
	s_and_b64 exec, exec, vcc
	global_load_dwordx4 v[228:231], v[22:23], off
	v_add_u32_e32 v26, 1, v26
	v_cmp_lt_i32_e32 vcc, v26, v25
	v_lshl_add_u64 v[22:23], v[22:23], 0, s[92:93]
	s_and_b64 exec, exec, vcc
	global_load_dwordx4 v[232:235], v[22:23], off
	v_add_u32_e32 v26, 1, v26
	v_cmp_lt_i32_e32 vcc, v26, v25
	v_lshl_add_u64 v[22:23], v[22:23], 0, s[92:93]
	s_and_b64 exec, exec, vcc
	global_load_dwordx4 v[236:239], v[22:23], off
	v_add_u32_e32 v26, 1, v26
	v_cmp_lt_i32_e32 vcc, v26, v25
	v_lshl_add_u64 v[22:23], v[22:23], 0, s[92:93]
	s_and_b64 exec, exec, vcc
	global_load_dwordx4 v[240:243], v[22:23], off
	v_add_u32_e32 v26, 1, v26
	v_cmp_lt_i32_e32 vcc, v26, v25
	v_lshl_add_u64 v[22:23], v[22:23], 0, s[92:93]
	s_and_b64 exec, exec, vcc
	global_load_dwordx4 v[244:247], v[22:23], off
	v_add_u32_e32 v26, 1, v26
	v_cmp_lt_i32_e32 vcc, v26, v25
	v_lshl_add_u64 v[22:23], v[22:23], 0, s[92:93]
	s_and_b64 exec, exec, vcc
	global_load_dwordx4 v[248:251], v[22:23], off
	v_add_u32_e32 v26, 1, v26
	v_cmp_lt_i32_e32 vcc, v26, v25
	v_lshl_add_u64 v[22:23], v[22:23], 0, s[92:93]
	s_and_b64 exec, exec, vcc
	global_load_dwordx4 v[130:133], v[22:23], off
	v_add_u32_e32 v26, 1, v26
	v_cmp_lt_i32_e32 vcc, v26, v25
	v_lshl_add_u64 v[22:23], v[22:23], 0, s[92:93]
	s_and_b64 exec, exec, vcc
	global_load_dwordx4 v[134:137], v[22:23], off
	v_add_u32_e32 v26, 1, v26
	v_cmp_lt_i32_e32 vcc, v26, v25
	v_lshl_add_u64 v[22:23], v[22:23], 0, s[92:93]
	s_and_b64 exec, exec, vcc
	global_load_dwordx4 v[138:141], v[22:23], off
	v_add_u32_e32 v26, 1, v26
	v_cmp_lt_i32_e32 vcc, v26, v25
	v_lshl_add_u64 v[22:23], v[22:23], 0, s[92:93]
	s_and_b64 exec, exec, vcc
	global_load_dwordx4 v[142:145], v[22:23], off
	v_add_u32_e32 v26, 1, v26
	v_cmp_lt_i32_e32 vcc, v26, v25
	v_lshl_add_u64 v[22:23], v[22:23], 0, s[92:93]
	s_and_b64 exec, exec, vcc
	global_load_dwordx4 v[146:149], v[22:23], off
	v_add_u32_e32 v26, 1, v26
	v_cmp_lt_i32_e32 vcc, v26, v25
	v_lshl_add_u64 v[22:23], v[22:23], 0, s[92:93]
	s_and_b64 exec, exec, vcc
	global_load_dwordx4 v[154:157], v[22:23], off
	v_add_u32_e32 v26, 1, v26
	v_cmp_lt_i32_e32 vcc, v26, v25
	v_lshl_add_u64 v[22:23], v[22:23], 0, s[92:93]
	s_and_b64 exec, exec, vcc
	global_load_dwordx4 v[158:161], v[22:23], off
	s_mov_b64 exec, s[100:101]
	s_waitcnt vmcnt(15)
; __device__ __forceinline__ float bf2f(bf16_t b) { return __uint_as_float(((unsigned)b) << 16); }
; __global__ void __launch_bounds__(NTHREADS) fwd_megakernel(Params p) {
;     ...
;             for (int k = lo; k < hi; ++k) {
;               bf16x8 v = *reinterpret_cast<const bf16x8*>(base + (long)k * 256);
; #pragma unroll
;               for (int j = 0; j < 8; ++j) sum[j] += bf2f((bf16_t)v[j]);
	v_and_b32_e32 v33, 0xffff0000, v216
	v_lshlrev_b32_e32 v32, 16, v216
	v_pk_add_f32 v[20:21], v[20:21], v[32:33]
	v_and_b32_e32 v33, 0xffff0000, v217
	v_lshlrev_b32_e32 v32, 16, v217
	v_and_b32_e32 v29, 0xffff0000, v218
	v_lshlrev_b32_e32 v28, 16, v218
	v_pk_add_f32 v[16:17], v[16:17], v[28:29]
	v_and_b32_e32 v29, 0xffff0000, v219
	v_lshlrev_b32_e32 v28, 16, v219
	v_pk_add_f32 v[18:19], v[18:19], v[32:33]
	v_pk_add_f32 v[2:3], v[2:3], v[28:29]
	s_waitcnt vmcnt(14)
	v_and_b32_e32 v33, 0xffff0000, v220
	v_lshlrev_b32_e32 v32, 16, v220
	v_pk_add_f32 v[20:21], v[20:21], v[32:33]
	v_and_b32_e32 v33, 0xffff0000, v221
	v_lshlrev_b32_e32 v32, 16, v221
	v_and_b32_e32 v29, 0xffff0000, v222
	v_lshlrev_b32_e32 v28, 16, v222
	v_pk_add_f32 v[16:17], v[16:17], v[28:29]
	v_and_b32_e32 v29, 0xffff0000, v223
	v_lshlrev_b32_e32 v28, 16, v223
	v_pk_add_f32 v[18:19], v[18:19], v[32:33]
	v_pk_add_f32 v[2:3], v[2:3], v[28:29]
	s_waitcnt vmcnt(13)
	v_and_b32_e32 v33, 0xffff0000, v224
	v_lshlrev_b32_e32 v32, 16, v224
	v_pk_add_f32 v[20:21], v[20:21], v[32:33]
	v_and_b32_e32 v33, 0xffff0000, v225
	v_lshlrev_b32_e32 v32, 16, v225
	v_and_b32_e32 v29, 0xffff0000, v226
	v_lshlrev_b32_e32 v28, 16, v226
	v_pk_add_f32 v[16:17], v[16:17], v[28:29]
	v_and_b32_e32 v29, 0xffff0000, v227
	v_lshlrev_b32_e32 v28, 16, v227
	v_pk_add_f32 v[18:19], v[18:19], v[32:33]
	v_pk_add_f32 v[2:3], v[2:3], v[28:29]
	s_waitcnt vmcnt(12)
	v_and_b32_e32 v33, 0xffff0000, v228
	v_lshlrev_b32_e32 v32, 16, v228
	v_pk_add_f32 v[20:21], v[20:21], v[32:33]
	v_and_b32_e32 v33, 0xffff0000, v229
	v_lshlrev_b32_e32 v32, 16, v229
	v_and_b32_e32 v29, 0xffff0000, v230
	v_lshlrev_b32_e32 v28, 16, v230
	v_pk_add_f32 v[16:17], v[16:17], v[28:29]
	v_and_b32_e32 v29, 0xffff0000, v231
	v_lshlrev_b32_e32 v28, 16, v231
	v_pk_add_f32 v[18:19], v[18:19], v[32:33]
	v_pk_add_f32 v[2:3], v[2:3], v[28:29]
	s_waitcnt vmcnt(11)
	v_and_b32_e32 v33, 0xffff0000, v232
	v_lshlrev_b32_e32 v32, 16, v232
	v_pk_add_f32 v[20:21], v[20:21], v[32:33]
	v_and_b32_e32 v33, 0xffff0000, v233
	v_lshlrev_b32_e32 v32, 16, v233
	v_and_b32_e32 v29, 0xffff0000, v234
	v_lshlrev_b32_e32 v28, 16, v234
	v_pk_add_f32 v[16:17], v[16:17], v[28:29]
	v_and_b32_e32 v29, 0xffff0000, v235
	v_lshlrev_b32_e32 v28, 16, v235
	v_pk_add_f32 v[18:19], v[18:19], v[32:33]
	v_pk_add_f32 v[2:3], v[2:3], v[28:29]
	s_waitcnt vmcnt(10)
	v_and_b32_e32 v33, 0xffff0000, v236
	v_lshlrev_b32_e32 v32, 16, v236
	v_pk_add_f32 v[20:21], v[20:21], v[32:33]
	v_and_b32_e32 v33, 0xffff0000, v237
	v_lshlrev_b32_e32 v32, 16, v237
	v_and_b32_e32 v29, 0xffff0000, v238
	v_lshlrev_b32_e32 v28, 16, v238
	v_pk_add_f32 v[16:17], v[16:17], v[28:29]
	v_and_b32_e32 v29, 0xffff0000, v239
	v_lshlrev_b32_e32 v28, 16, v239
	v_pk_add_f32 v[18:19], v[18:19], v[32:33]
	v_pk_add_f32 v[2:3], v[2:3], v[28:29]
	s_waitcnt vmcnt(9)
	v_and_b32_e32 v33, 0xffff0000, v240
	v_lshlrev_b32_e32 v32, 16, v240
	v_pk_add_f32 v[20:21], v[20:21], v[32:33]
	v_and_b32_e32 v33, 0xffff0000, v241
	v_lshlrev_b32_e32 v32, 16, v241
	v_and_b32_e32 v29, 0xffff0000, v242
	v_lshlrev_b32_e32 v28, 16, v242
	v_pk_add_f32 v[16:17], v[16:17], v[28:29]
	v_and_b32_e32 v29, 0xffff0000, v243
	v_lshlrev_b32_e32 v28, 16, v243
	v_pk_add_f32 v[18:19], v[18:19], v[32:33]
	v_pk_add_f32 v[2:3], v[2:3], v[28:29]
	s_waitcnt vmcnt(8)
	v_and_b32_e32 v33, 0xffff0000, v244
	v_lshlrev_b32_e32 v32, 16, v244
	v_pk_add_f32 v[20:21], v[20:21], v[32:33]
	v_and_b32_e32 v33, 0xffff0000, v245
	v_lshlrev_b32_e32 v32, 16, v245
	v_and_b32_e32 v29, 0xffff0000, v246
	v_lshlrev_b32_e32 v28, 16, v246
	v_pk_add_f32 v[16:17], v[16:17], v[28:29]
	v_and_b32_e32 v29, 0xffff0000, v247
	v_lshlrev_b32_e32 v28, 16, v247
	v_pk_add_f32 v[18:19], v[18:19], v[32:33]
	v_pk_add_f32 v[2:3], v[2:3], v[28:29]
	s_waitcnt vmcnt(7)
; __device__ __forceinline__ float bf2f(bf16_t b) { return __uint_as_float(((unsigned)b) << 16); }
; __global__ void __launch_bounds__(NTHREADS) fwd_megakernel(Params p) {
;     ...
;             for (int k = lo; k < hi; ++k) {
;               bf16x8 v = *reinterpret_cast<const bf16x8*>(base + (long)k * 256);
; #pragma unroll
;               for (int j = 0; j < 8; ++j) sum[j] += bf2f((bf16_t)v[j]);
	v_and_b32_e32 v33, 0xffff0000, v248
	v_lshlrev_b32_e32 v32, 16, v248
	v_pk_add_f32 v[20:21], v[20:21], v[32:33]
	v_and_b32_e32 v33, 0xffff0000, v249
	v_lshlrev_b32_e32 v32, 16, v249
	v_and_b32_e32 v29, 0xffff0000, v250
	v_lshlrev_b32_e32 v28, 16, v250
	v_pk_add_f32 v[16:17], v[16:17], v[28:29]
	v_and_b32_e32 v29, 0xffff0000, v251
	v_lshlrev_b32_e32 v28, 16, v251
	v_pk_add_f32 v[18:19], v[18:19], v[32:33]
	v_pk_add_f32 v[2:3], v[2:3], v[28:29]
	s_waitcnt vmcnt(6)
	v_and_b32_e32 v33, 0xffff0000, v130
	v_lshlrev_b32_e32 v32, 16, v130
	v_pk_add_f32 v[20:21], v[20:21], v[32:33]
	v_and_b32_e32 v33, 0xffff0000, v131
	v_lshlrev_b32_e32 v32, 16, v131
	v_and_b32_e32 v29, 0xffff0000, v132
	v_lshlrev_b32_e32 v28, 16, v132
	v_pk_add_f32 v[16:17], v[16:17], v[28:29]
	v_and_b32_e32 v29, 0xffff0000, v133
	v_lshlrev_b32_e32 v28, 16, v133
	v_pk_add_f32 v[18:19], v[18:19], v[32:33]
	v_pk_add_f32 v[2:3], v[2:3], v[28:29]
	s_waitcnt vmcnt(5)
	v_and_b32_e32 v33, 0xffff0000, v134
	v_lshlrev_b32_e32 v32, 16, v134
	v_pk_add_f32 v[20:21], v[20:21], v[32:33]
	v_and_b32_e32 v33, 0xffff0000, v135
	v_lshlrev_b32_e32 v32, 16, v135
	v_and_b32_e32 v29, 0xffff0000, v136
	v_lshlrev_b32_e32 v28, 16, v136
	v_pk_add_f32 v[16:17], v[16:17], v[28:29]
	v_and_b32_e32 v29, 0xffff0000, v137
	v_lshlrev_b32_e32 v28, 16, v137
	v_pk_add_f32 v[18:19], v[18:19], v[32:33]
	v_pk_add_f32 v[2:3], v[2:3], v[28:29]
	s_waitcnt vmcnt(4)
	v_and_b32_e32 v33, 0xffff0000, v138
	v_lshlrev_b32_e32 v32, 16, v138
	v_pk_add_f32 v[20:21], v[20:21], v[32:33]
	v_and_b32_e32 v33, 0xffff0000, v139
	v_lshlrev_b32_e32 v32, 16, v139
	v_and_b32_e32 v29, 0xffff0000, v140
	v_lshlrev_b32_e32 v28, 16, v140
	v_pk_add_f32 v[16:17], v[16:17], v[28:29]
	v_and_b32_e32 v29, 0xffff0000, v141
	v_lshlrev_b32_e32 v28, 16, v141
	v_pk_add_f32 v[18:19], v[18:19], v[32:33]
	v_pk_add_f32 v[2:3], v[2:3], v[28:29]
	s_waitcnt vmcnt(3)
	v_and_b32_e32 v33, 0xffff0000, v142
	v_lshlrev_b32_e32 v32, 16, v142
	v_pk_add_f32 v[20:21], v[20:21], v[32:33]
	v_and_b32_e32 v33, 0xffff0000, v143
	v_lshlrev_b32_e32 v32, 16, v143
	v_and_b32_e32 v29, 0xffff0000, v144
	v_lshlrev_b32_e32 v28, 16, v144
	v_pk_add_f32 v[16:17], v[16:17], v[28:29]
	v_and_b32_e32 v29, 0xffff0000, v145
	v_lshlrev_b32_e32 v28, 16, v145
	v_pk_add_f32 v[18:19], v[18:19], v[32:33]
	v_pk_add_f32 v[2:3], v[2:3], v[28:29]
	s_waitcnt vmcnt(2)
	v_and_b32_e32 v33, 0xffff0000, v146
	v_lshlrev_b32_e32 v32, 16, v146
	v_pk_add_f32 v[20:21], v[20:21], v[32:33]
	v_and_b32_e32 v33, 0xffff0000, v147
	v_lshlrev_b32_e32 v32, 16, v147
	v_and_b32_e32 v29, 0xffff0000, v148
	v_lshlrev_b32_e32 v28, 16, v148
	v_pk_add_f32 v[16:17], v[16:17], v[28:29]
	v_and_b32_e32 v29, 0xffff0000, v149
	v_lshlrev_b32_e32 v28, 16, v149
	v_pk_add_f32 v[18:19], v[18:19], v[32:33]
	v_pk_add_f32 v[2:3], v[2:3], v[28:29]
	s_waitcnt vmcnt(1)
	v_and_b32_e32 v33, 0xffff0000, v154
	v_lshlrev_b32_e32 v32, 16, v154
	v_pk_add_f32 v[20:21], v[20:21], v[32:33]
	v_and_b32_e32 v33, 0xffff0000, v155
	v_lshlrev_b32_e32 v32, 16, v155
	v_and_b32_e32 v29, 0xffff0000, v156
	v_lshlrev_b32_e32 v28, 16, v156
	v_pk_add_f32 v[16:17], v[16:17], v[28:29]
	v_and_b32_e32 v29, 0xffff0000, v157
	v_lshlrev_b32_e32 v28, 16, v157
	v_pk_add_f32 v[18:19], v[18:19], v[32:33]
	v_pk_add_f32 v[2:3], v[2:3], v[28:29]
	s_waitcnt vmcnt(0)
	v_and_b32_e32 v33, 0xffff0000, v158
	v_lshlrev_b32_e32 v32, 16, v158
	v_pk_add_f32 v[20:21], v[20:21], v[32:33]
	v_and_b32_e32 v33, 0xffff0000, v159
	v_lshlrev_b32_e32 v32, 16, v159
	v_and_b32_e32 v29, 0xffff0000, v160
	v_lshlrev_b32_e32 v28, 16, v160
	v_pk_add_f32 v[16:17], v[16:17], v[28:29]
	v_and_b32_e32 v29, 0xffff0000, v161
	v_lshlrev_b32_e32 v28, 16, v161
	v_pk_add_f32 v[18:19], v[18:19], v[32:33]
	v_pk_add_f32 v[2:3], v[2:3], v[28:29]
